# write-through (sc1) stores also in the prologue phase P0 (lighter L2 flush at the first grid barrier)
# speedup vs baseline: 1.1846x; 1.0041x over previous
; #define LAS __attribute__((address_space(3)))
; __device__ __forceinline__ unsigned pk_bf16(float lo, float hi) { return pg8::cvt_pk_bf16(lo, hi); }
; #define lane lane_id()
; __device__ __forceinline__ void tr_store(int K, int N, bf16_t* __restrict__ WT, const LAS float* scr, int item, int lane, const float* __restrict__ gk, bool gmlp_perm) {
;     const int nblk = N / 64, k0 = 64 * (item / nblk), n0 = 64 * (item % nblk);
;     int r0 = n0;
;     if (gmlp_perm) {
;         if (n0 < GW) { const int cb = n0 >> 7; r0 = 256 * (3 * (cb >> 1) + (cb & 1)) + (n0 & 127); }
;         else if (n0 < 2 * GW) { const int mv = n0 - GW; r0 = 256 * (3 * (mv >> 8) + 2) + (mv & 255); }
;         else { const int mz = n0 - 2 * GW, cb = mz >> 7; r0 = 256 * (3 * (cb >> 1) + (cb & 1)) + 128 + (mz & 127); }
;     }
;     const int c = lane & 7;
;     f32x4 ga = {1.f, 1.f, 1.f, 1.f}, gb = {1.f, 1.f, 1.f, 1.f};
;     if (gk) { ga = *(const f32x4*)(gk + k0 + 8 * c); gb = *(const f32x4*)(gk + k0 + 8 * c + 4); }
; #pragma unroll
;     for (int j = 0; j < 8; ++j) { const int nn = (lane >> 3) + 8 * j; const LAS float* s = scr + (8 * c) * 65 + nn;
;         u32x4 o; o.x = pk_bf16(s[0] * ga[0], s[65] * ga[1]); o.y = pk_bf16(s[2 * 65] * ga[2], s[3 * 65] * ga[3]); o.z = pk_bf16(s[4 * 65] * gb[0], s[5 * 65] * gb[1]); o.w = pk_bf16(s[6 * 65] * gb[2], s[7 * 65] * gb[3]);
;         *(u32x4*)(WT + (size_t)(r0 + nn) * K + k0 + 8 * c) = o; }
;     asm volatile("s_waitcnt lgkmcnt(0)" ::: "memory");
; }
.LBB0_24:
	ds_read2_b32 v[78:79], v82 offset1:65
	v_add_u32_e32 v94, 0x400, v82
	v_add_u32_e32 v90, s14, v81
	v_ashrrev_i32_e32 v91, 31, v90
	v_lshlrev_b64 v[92:93], 12, v[90:91]
	s_waitcnt vmcnt(0) lgkmcnt(0)
	v_mul_f32_e32 v78, v68, v78
	v_mul_f32_e32 v79, v69, v79
	v_cvt_pk_bf16_f32 v84, v78, v79
	ds_read2_b32 v[78:79], v82 offset0:130 offset1:195
	s_add_i32 s11, s11, s12
	s_andn2_b64 vcc, exec, s[4:5]
	s_waitcnt lgkmcnt(0)
	v_mul_f32_e32 v78, v70, v78
	v_mul_f32_e32 v79, v71, v79
	v_cvt_pk_bf16_f32 v85, v78, v79
	ds_read2_b32 v[78:79], v94 offset0:4 offset1:69
	s_waitcnt lgkmcnt(0)
	v_mul_f32_e32 v78, v64, v78
	v_mul_f32_e32 v79, v65, v79
	v_cvt_pk_bf16_f32 v86, v78, v79
	ds_read2_b32 v[88:89], v94 offset0:134 offset1:199
	v_lshl_add_u64 v[78:79], s[8:9], 1, v[76:77]
	v_lshl_add_u64 v[92:93], v[78:79], 0, v[92:93]
	s_mov_b32 s8, s13
	s_waitcnt lgkmcnt(0)
	v_mul_f32_e32 v87, v66, v88
	v_mul_f32_e32 v88, v67, v89
	v_cvt_pk_bf16_f32 v87, v87, v88
	ds_read2_b32 v[88:89], v82 offset0:8 offset1:73
	global_store_dwordx4 v[92:93], v[84:87], off sc1
	v_add_u32_e32 v92, 8, v90
	v_ashrrev_i32_e32 v93, 31, v92
	v_lshlrev_b64 v[92:93], 12, v[92:93]
	s_waitcnt lgkmcnt(0)
	v_mul_f32_e32 v84, v68, v88
	v_mul_f32_e32 v85, v69, v89
	v_cvt_pk_bf16_f32 v84, v84, v85
	ds_read2_b32 v[86:87], v82 offset0:138 offset1:203
	v_lshl_add_u64 v[92:93], v[78:79], 0, v[92:93]
	s_waitcnt lgkmcnt(0)
	v_mul_f32_e32 v85, v70, v86
	v_mul_f32_e32 v86, v71, v87
	v_cvt_pk_bf16_f32 v85, v85, v86
	ds_read2_b32 v[86:87], v94 offset0:12 offset1:77
	s_waitcnt lgkmcnt(0)
	v_mul_f32_e32 v86, v64, v86
	v_mul_f32_e32 v87, v65, v87
	v_cvt_pk_bf16_f32 v86, v86, v87
	ds_read2_b32 v[88:89], v94 offset0:142 offset1:207
	s_waitcnt lgkmcnt(0)
	v_mul_f32_e32 v87, v66, v88
	v_mul_f32_e32 v88, v67, v89
	v_cvt_pk_bf16_f32 v87, v87, v88
	ds_read2_b32 v[88:89], v82 offset0:16 offset1:81
	global_store_dwordx4 v[92:93], v[84:87], off sc1
	v_add_u32_e32 v92, 16, v90
	v_ashrrev_i32_e32 v93, 31, v92
	v_lshlrev_b64 v[92:93], 12, v[92:93]
	s_waitcnt lgkmcnt(0)
	v_mul_f32_e32 v84, v68, v88
	v_mul_f32_e32 v85, v69, v89
	v_cvt_pk_bf16_f32 v84, v84, v85
	ds_read2_b32 v[86:87], v82 offset0:146 offset1:211
	v_lshl_add_u64 v[92:93], v[78:79], 0, v[92:93]
	s_waitcnt lgkmcnt(0)
	v_mul_f32_e32 v85, v70, v86
	v_mul_f32_e32 v86, v71, v87
	v_cvt_pk_bf16_f32 v85, v85, v86
	ds_read2_b32 v[86:87], v94 offset0:20 offset1:85
	s_waitcnt lgkmcnt(0)
	v_mul_f32_e32 v86, v64, v86
	v_mul_f32_e32 v87, v65, v87
	v_cvt_pk_bf16_f32 v86, v86, v87
	ds_read2_b32 v[88:89], v94 offset0:150 offset1:215
	s_waitcnt lgkmcnt(0)
	v_mul_f32_e32 v87, v66, v88
	v_mul_f32_e32 v88, v67, v89
	v_cvt_pk_bf16_f32 v87, v87, v88
	ds_read2_b32 v[88:89], v82 offset0:24 offset1:89
	global_store_dwordx4 v[92:93], v[84:87], off sc1
	v_add_u32_e32 v92, 24, v90
	v_ashrrev_i32_e32 v93, 31, v92
	v_lshlrev_b64 v[92:93], 12, v[92:93]
	s_waitcnt lgkmcnt(0)
	v_mul_f32_e32 v84, v68, v88
	v_mul_f32_e32 v85, v69, v89
	v_cvt_pk_bf16_f32 v84, v84, v85
	ds_read2_b32 v[86:87], v82 offset0:154 offset1:219
	v_lshl_add_u64 v[92:93], v[78:79], 0, v[92:93]
	s_waitcnt lgkmcnt(0)
	v_mul_f32_e32 v85, v70, v86
	v_mul_f32_e32 v86, v71, v87
	v_cvt_pk_bf16_f32 v85, v85, v86
	ds_read2_b32 v[86:87], v94 offset0:28 offset1:93
	s_waitcnt lgkmcnt(0)
	v_mul_f32_e32 v86, v64, v86
	v_mul_f32_e32 v87, v65, v87
	v_cvt_pk_bf16_f32 v86, v86, v87
	ds_read2_b32 v[88:89], v94 offset0:158 offset1:223
	s_waitcnt lgkmcnt(0)
	v_mul_f32_e32 v87, v66, v88
	v_mul_f32_e32 v88, v67, v89
	v_cvt_pk_bf16_f32 v87, v87, v88
	ds_read2_b32 v[88:89], v82 offset0:32 offset1:97
	global_store_dwordx4 v[92:93], v[84:87], off sc1
	v_add_u32_e32 v92, 32, v90
	v_ashrrev_i32_e32 v93, 31, v92
	v_lshlrev_b64 v[92:93], 12, v[92:93]
	s_waitcnt lgkmcnt(0)
	v_mul_f32_e32 v84, v68, v88
	v_mul_f32_e32 v85, v69, v89
	v_cvt_pk_bf16_f32 v84, v84, v85
	ds_read2_b32 v[86:87], v82 offset0:162 offset1:227
	v_lshl_add_u64 v[92:93], v[78:79], 0, v[92:93]
	s_waitcnt lgkmcnt(0)
	v_mul_f32_e32 v85, v70, v86
	v_mul_f32_e32 v86, v71, v87
	v_cvt_pk_bf16_f32 v85, v85, v86
	ds_read2_b32 v[86:87], v94 offset0:36 offset1:101
	s_waitcnt lgkmcnt(0)
	v_mul_f32_e32 v86, v64, v86
	v_mul_f32_e32 v87, v65, v87
	v_cvt_pk_bf16_f32 v86, v86, v87
	ds_read2_b32 v[88:89], v94 offset0:166 offset1:231
	s_waitcnt lgkmcnt(0)
	v_mul_f32_e32 v87, v66, v88
	v_mul_f32_e32 v88, v67, v89
	v_cvt_pk_bf16_f32 v87, v87, v88
	ds_read2_b32 v[88:89], v82 offset0:40 offset1:105
	global_store_dwordx4 v[92:93], v[84:87], off sc1
	v_add_u32_e32 v92, 40, v90
	v_ashrrev_i32_e32 v93, 31, v92
	v_lshlrev_b64 v[92:93], 12, v[92:93]
	s_waitcnt lgkmcnt(0)
	v_mul_f32_e32 v84, v68, v88
	v_mul_f32_e32 v85, v69, v89
	v_cvt_pk_bf16_f32 v84, v84, v85
	ds_read2_b32 v[86:87], v82 offset0:170 offset1:235
	v_lshl_add_u64 v[92:93], v[78:79], 0, v[92:93]
	s_waitcnt lgkmcnt(0)
	v_mul_f32_e32 v85, v70, v86
	v_mul_f32_e32 v86, v71, v87
	v_cvt_pk_bf16_f32 v85, v85, v86
	ds_read2_b32 v[86:87], v94 offset0:44 offset1:109
	s_waitcnt lgkmcnt(0)
	v_mul_f32_e32 v86, v64, v86
	v_mul_f32_e32 v87, v65, v87
	v_cvt_pk_bf16_f32 v86, v86, v87
	ds_read2_b32 v[88:89], v94 offset0:174 offset1:239
	s_waitcnt lgkmcnt(0)
	v_mul_f32_e32 v87, v66, v88
	v_mul_f32_e32 v88, v67, v89
	v_cvt_pk_bf16_f32 v87, v87, v88
	ds_read2_b32 v[88:89], v82 offset0:48 offset1:113
	global_store_dwordx4 v[92:93], v[84:87], off sc1
	v_add_u32_e32 v92, 48, v90
	v_ashrrev_i32_e32 v93, 31, v92
	v_lshlrev_b64 v[92:93], 12, v[92:93]
	s_waitcnt lgkmcnt(0)
	v_mul_f32_e32 v84, v68, v88
	v_mul_f32_e32 v85, v69, v89
	v_cvt_pk_bf16_f32 v84, v84, v85
	ds_read2_b32 v[86:87], v82 offset0:178 offset1:243
	v_lshl_add_u64 v[92:93], v[78:79], 0, v[92:93]
	s_waitcnt lgkmcnt(0)
	v_mul_f32_e32 v85, v70, v86
	v_mul_f32_e32 v86, v71, v87
	v_cvt_pk_bf16_f32 v85, v85, v86
	ds_read2_b32 v[86:87], v94 offset0:52 offset1:117
	s_waitcnt lgkmcnt(0)
	v_mul_f32_e32 v86, v64, v86
	v_mul_f32_e32 v87, v65, v87
	v_cvt_pk_bf16_f32 v86, v86, v87
	ds_read2_b32 v[88:89], v94 offset0:182 offset1:247
	s_waitcnt lgkmcnt(0)
	v_mul_f32_e32 v87, v66, v88
	v_mul_f32_e32 v88, v67, v89
	v_cvt_pk_bf16_f32 v87, v87, v88
	ds_read2_b32 v[88:89], v82 offset0:56 offset1:121
	global_store_dwordx4 v[92:93], v[84:87], off sc1
	s_waitcnt lgkmcnt(0)
	v_mul_f32_e32 v68, v68, v88
	v_mul_f32_e32 v69, v69, v89
	v_cvt_pk_bf16_f32 v68, v68, v69
	ds_read2_b32 v[84:85], v82 offset0:186 offset1:251
	s_waitcnt lgkmcnt(0)
	v_mul_f32_e32 v69, v70, v84
	v_mul_f32_e32 v70, v71, v85
	v_cvt_pk_bf16_f32 v69, v69, v70
	ds_read2_b32 v[70:71], v94 offset0:60 offset1:125
	v_add_u32_e32 v84, 56, v90
	v_ashrrev_i32_e32 v85, 31, v84
	v_lshlrev_b64 v[84:85], 12, v[84:85]
	v_lshl_add_u64 v[78:79], v[78:79], 0, v[84:85]
	s_waitcnt lgkmcnt(0)
	v_mul_f32_e32 v64, v64, v70
	v_mul_f32_e32 v65, v65, v71
	v_cvt_pk_bf16_f32 v70, v64, v65
	ds_read2_b32 v[64:65], v94 offset0:190 offset1:255
	s_waitcnt lgkmcnt(0)
	v_mul_f32_e32 v64, v66, v64
	v_mul_f32_e32 v65, v67, v65
	v_cvt_pk_bf16_f32 v71, v64, v65
	global_store_dwordx4 v[78:79], v[68:71], off sc1
	s_waitcnt lgkmcnt(0)
	s_cbranch_vccz .LBB0_36

; __device__ __forceinline__ unsigned pk_bf16(float lo, float hi) { return pg8::cvt_pk_bf16(lo, hi); }
; #define lane lane_id()
; __global__ void __launch_bounds__(NWAVES * 64, 2) fwd_kernel(Args a) {
;     ...
;             const float ms = wave_sum(ss) * (1.0f / DM) + EPS, ms2 = wave_sum(ss2) * (1.0f / DM) + EPS;
;             const float rstd = __builtin_amdgcn_rsqf(ms), rstd2 = __builtin_amdgcn_rsqf(ms2);
;             if (lane == 0) { IRS0[m] = __builtin_amdgcn_sqrtf(ms); if (two) IRS0[m2] = __builtin_amdgcn_sqrtf(ms2); }
;             u32x2* o8 = (u32x2*)(HN0 + (size_t)m * DM) + lane; u32x2* o82 = (u32x2*)(HN0 + (size_t)m2 * DM) + lane;
; #pragma unroll
;             for (int j = 0; j < 8; ++j) {
;                 u32x2 w; w.x = pk_bf16(v[j][0] * rstd, v[j][1] * rstd); w.y = pk_bf16(v[j][2] * rstd, v[j][3] * rstd); o8[64 * j] = w;
;                 if (two) { u32x2 w2; w2.x = pk_bf16(v2[j][0] * rstd2, v2[j][1] * rstd2); w2.y = pk_bf16(v2[j][2] * rstd2, v2[j][3] * rstd2); o82[64 * j] = w2; } }
.LBB0_47:
	s_or_b64 exec, exec, s[14:15]
	v_rsq_f32_e32 v81, v70
	v_rsq_f32_e32 v80, v71
	s_lshl_b64 s[12:13], s[12:13], 11
	s_ashr_i32 s11, s10, 31
	v_lshl_add_u64 v[72:73], s[12:13], 1, v[68:69]
	s_lshl_b64 s[12:13], s[10:11], 12
	v_mul_f32_e32 v20, v81, v20
	v_mul_f32_e32 v21, v81, v21
	v_lshl_add_u64 v[70:71], v[68:69], 0, s[12:13]
	v_cvt_pk_bf16_f32 v20, v20, v21
	v_mul_f32_e32 v21, v81, v22
	s_and_b64 vcc, exec, s[4:5]
	v_mul_f32_e32 v22, v81, v23
	v_cvt_pk_bf16_f32 v21, v21, v22
	global_store_dwordx2 v[72:73], v[20:21], off sc1
	s_cbranch_vccnz .LBB0_49
	v_mul_f32_e32 v20, v80, v60
	v_mul_f32_e32 v21, v80, v61
	v_cvt_pk_bf16_f32 v20, v20, v21
	v_mul_f32_e32 v21, v80, v62
	v_mul_f32_e32 v22, v80, v63
	v_cvt_pk_bf16_f32 v21, v21, v22
	global_store_dwordx2 v[70:71], v[20:21], off sc1
.LBB0_49:
	v_mul_f32_e32 v16, v81, v16
	v_mul_f32_e32 v17, v81, v17
	v_cvt_pk_bf16_f32 v16, v16, v17
	v_mul_f32_e32 v17, v81, v18
	s_and_b64 vcc, exec, s[4:5]
	v_mul_f32_e32 v18, v81, v19
	v_cvt_pk_bf16_f32 v17, v17, v18
	global_store_dwordx2 v[72:73], v[16:17], off offset:512 sc1
	s_cbranch_vccnz .LBB0_51
	v_mul_f32_e32 v16, v80, v56
	v_mul_f32_e32 v17, v80, v57
	v_cvt_pk_bf16_f32 v16, v16, v17
	v_mul_f32_e32 v17, v80, v58
	v_mul_f32_e32 v18, v80, v59
	v_cvt_pk_bf16_f32 v17, v17, v18
	global_store_dwordx2 v[70:71], v[16:17], off offset:512 sc1
.LBB0_51:
	v_mul_f32_e32 v12, v81, v12
	v_mul_f32_e32 v13, v81, v13
	v_cvt_pk_bf16_f32 v12, v12, v13
	v_mul_f32_e32 v13, v81, v14
	s_and_b64 vcc, exec, s[4:5]
	v_mul_f32_e32 v14, v81, v15
	v_cvt_pk_bf16_f32 v13, v13, v14
	global_store_dwordx2 v[72:73], v[12:13], off offset:1024 sc1
	s_cbranch_vccnz .LBB0_53
	v_mul_f32_e32 v12, v80, v52
	v_mul_f32_e32 v13, v80, v53
	v_cvt_pk_bf16_f32 v12, v12, v13
	v_mul_f32_e32 v13, v80, v54
	v_mul_f32_e32 v14, v80, v55
	v_cvt_pk_bf16_f32 v13, v13, v14
	global_store_dwordx2 v[70:71], v[12:13], off offset:1024 sc1
.LBB0_53:
	v_mul_f32_e32 v8, v81, v8
	v_mul_f32_e32 v9, v81, v9
	v_cvt_pk_bf16_f32 v8, v8, v9
	v_mul_f32_e32 v9, v81, v10
	s_and_b64 vcc, exec, s[4:5]
	v_mul_f32_e32 v10, v81, v11
	v_cvt_pk_bf16_f32 v9, v9, v10
	global_store_dwordx2 v[72:73], v[8:9], off offset:1536 sc1
	s_cbranch_vccnz .LBB0_55
	v_mul_f32_e32 v8, v80, v48
	v_mul_f32_e32 v9, v80, v49
	v_cvt_pk_bf16_f32 v8, v8, v9
	v_mul_f32_e32 v9, v80, v50
	v_mul_f32_e32 v10, v80, v51
	v_cvt_pk_bf16_f32 v9, v9, v10
	global_store_dwordx2 v[70:71], v[8:9], off offset:1536 sc1
.LBB0_55:
	v_mul_f32_e32 v4, v81, v4
	v_mul_f32_e32 v5, v81, v5
	v_cvt_pk_bf16_f32 v4, v4, v5
	v_mul_f32_e32 v5, v81, v6
	s_and_b64 vcc, exec, s[4:5]
	v_mul_f32_e32 v6, v81, v7
	v_cvt_pk_bf16_f32 v5, v5, v6
	global_store_dwordx2 v[72:73], v[4:5], off offset:2048 sc1
	s_cbranch_vccnz .LBB0_57
	v_mul_f32_e32 v4, v80, v44
	v_mul_f32_e32 v5, v80, v45
	v_cvt_pk_bf16_f32 v4, v4, v5
	v_mul_f32_e32 v5, v80, v46
	v_mul_f32_e32 v6, v80, v47
	v_cvt_pk_bf16_f32 v5, v5, v6
	global_store_dwordx2 v[70:71], v[4:5], off offset:2048 sc1
.LBB0_57:
	v_mul_f32_e32 v0, v81, v0
	v_mul_f32_e32 v1, v81, v1
	v_cvt_pk_bf16_f32 v0, v0, v1
	v_mul_f32_e32 v1, v81, v2
	s_and_b64 vcc, exec, s[4:5]
	v_mul_f32_e32 v2, v81, v3
	v_cvt_pk_bf16_f32 v1, v1, v2
	global_store_dwordx2 v[72:73], v[0:1], off offset:2560 sc1
	s_cbranch_vccnz .LBB0_59
	v_mul_f32_e32 v0, v80, v40
	v_mul_f32_e32 v1, v80, v41
	v_cvt_pk_bf16_f32 v0, v0, v1
	v_mul_f32_e32 v1, v80, v42
	v_mul_f32_e32 v2, v80, v43
	v_cvt_pk_bf16_f32 v1, v1, v2
	global_store_dwordx2 v[70:71], v[0:1], off offset:2560 sc1
.LBB0_59:
	v_mul_f32_e32 v0, v81, v36
	v_mul_f32_e32 v1, v81, v37
	v_cvt_pk_bf16_f32 v0, v0, v1
	v_mul_f32_e32 v1, v81, v38
	s_and_b64 vcc, exec, s[4:5]
	v_mul_f32_e32 v2, v81, v39
	v_cvt_pk_bf16_f32 v1, v1, v2
	global_store_dwordx2 v[72:73], v[0:1], off offset:3072 sc1
	s_cbranch_vccnz .LBB0_61
	v_mul_f32_e32 v0, v80, v32
	v_mul_f32_e32 v1, v80, v33
	v_cvt_pk_bf16_f32 v0, v0, v1
	v_mul_f32_e32 v1, v80, v34
	v_mul_f32_e32 v2, v80, v35
	v_cvt_pk_bf16_f32 v1, v1, v2
	global_store_dwordx2 v[70:71], v[0:1], off offset:3072 sc1
.LBB0_61:
	v_mul_f32_e32 v0, v81, v28
	v_mul_f32_e32 v1, v81, v29
	v_cvt_pk_bf16_f32 v0, v0, v1
	v_mul_f32_e32 v1, v81, v30
	s_and_b64 vcc, exec, s[4:5]
	v_mul_f32_e32 v2, v81, v31
	v_cvt_pk_bf16_f32 v1, v1, v2
	global_store_dwordx2 v[72:73], v[0:1], off offset:3584 sc1
	s_cbranch_vccnz .LBB0_43
	v_mul_f32_e32 v0, v80, v24
	v_mul_f32_e32 v1, v80, v25
	v_cvt_pk_bf16_f32 v0, v0, v1
	v_mul_f32_e32 v1, v80, v26
	v_mul_f32_e32 v2, v80, v27
	v_cvt_pk_bf16_f32 v1, v1, v2
	global_store_dwordx2 v[70:71], v[0:1], off offset:3584 sc1
	s_branch .LBB0_43
